# adds: DPP row reductions replace ds_bpermute butterflies (conv LayerNorm statistics incl. batched LDS partial reads; phase-0 rmsnorm row sums via v_readlane broadcast) - same add tree, bit-identical
# baseline (speedup 1.0000x reference)
; __device__ __forceinline__ float bf_lo(unsigned u) { return __uint_as_float(u << 16); }
; __device__ __forceinline__ float bf_hi(unsigned u) { return __uint_as_float(u & 0xffff0000u); }
; __device__ __forceinline__ void conv_run(LAS unsigned char* lds, const bf16_t* AG, bf16_t* CA, const float* cw, const float* cb, const float* lng, const float* lnb, int unit0, int nun, const int wave_s) {
;     ...
;         for (int j = 0; j < 31; ++j) { const unsigned wp = wl[j * 512 + tid]; const f32x2 w = (f32x2){bf_lo(wp), bf_hi(wp)};
; #pragma unroll
;             for (int t = 0; t < 16; ++t) acc[t] += w * in[t + j]; }
.LBB0_828:
	ds_read2st64_b32 v[150:151], v132 offset1:8
	v_readlane_b32 s13, v253, 26
	s_waitcnt lgkmcnt(0)
	v_lshlrev_b32_e32 v152, 16, v150
	v_and_b32_e32 v153, 0xffff0000, v150
	s_waitcnt vmcnt(2)
	v_pk_fma_f32 v[104:105], v[104:105], v[152:153], v[2:3]
	v_pk_fma_f32 v[154:155], v[90:91], v[152:153], v[2:3]
	v_pk_fma_f32 v[156:157], v[106:107], v[152:153], v[2:3]
	v_pk_fma_f32 v[158:159], v[92:93], v[152:153], v[2:3]
	v_pk_fma_f32 v[160:161], v[110:111], v[152:153], v[2:3]
	v_pk_fma_f32 v[162:163], v[94:95], v[152:153], v[2:3]
	v_pk_fma_f32 v[164:165], v[112:113], v[152:153], v[2:3]
	v_pk_fma_f32 v[166:167], v[96:97], v[152:153], v[2:3]
	v_pk_fma_f32 v[168:169], v[114:115], v[152:153], v[2:3]
	v_pk_fma_f32 v[170:171], v[98:99], v[152:153], v[2:3]
	v_pk_fma_f32 v[172:173], v[116:117], v[152:153], v[2:3]
	v_pk_fma_f32 v[174:175], v[100:101], v[152:153], v[2:3]
	v_lshlrev_b32_e32 v150, 16, v151
	v_and_b32_e32 v151, 0xffff0000, v151
	v_pk_fma_f32 v[90:91], v[90:91], v[150:151], v[104:105]
	v_pk_fma_f32 v[104:105], v[106:107], v[150:151], v[154:155]
	v_pk_fma_f32 v[154:155], v[92:93], v[150:151], v[156:157]
	v_pk_fma_f32 v[156:157], v[110:111], v[150:151], v[158:159]
	v_pk_fma_f32 v[158:159], v[94:95], v[150:151], v[160:161]
	v_pk_fma_f32 v[160:161], v[112:113], v[150:151], v[162:163]
	v_pk_fma_f32 v[162:163], v[96:97], v[150:151], v[164:165]
	v_pk_fma_f32 v[164:165], v[114:115], v[150:151], v[166:167]
	v_pk_fma_f32 v[166:167], v[98:99], v[150:151], v[168:169]
	v_pk_fma_f32 v[168:169], v[116:117], v[150:151], v[170:171]
	v_pk_fma_f32 v[170:171], v[100:101], v[150:151], v[172:173]
	v_pk_fma_f32 v[172:173], v[118:119], v[150:151], v[174:175]
	ds_read2st64_b32 v[174:175], v132 offset0:16 offset1:24
	v_pk_fma_f32 v[176:177], v[118:119], v[152:153], v[2:3]
	v_pk_fma_f32 v[178:179], v[102:103], v[152:153], v[2:3]
	v_pk_fma_f32 v[180:181], v[76:77], v[152:153], v[2:3]
	v_pk_fma_f32 v[152:153], v[130:131], v[152:153], v[2:3]
	v_pk_fma_f32 v[176:177], v[102:103], v[150:151], v[176:177]
	v_pk_fma_f32 v[178:179], v[76:77], v[150:151], v[178:179]
	v_pk_fma_f32 v[180:181], v[130:131], v[150:151], v[180:181]
	v_pk_fma_f32 v[150:151], v[128:129], v[150:151], v[152:153]
	s_waitcnt lgkmcnt(0)
	v_lshlrev_b32_e32 v152, 16, v174
	v_and_b32_e32 v153, 0xffff0000, v174
	v_pk_fma_f32 v[90:91], v[106:107], v[152:153], v[90:91]
	v_pk_fma_f32 v[104:105], v[92:93], v[152:153], v[104:105]
	v_pk_fma_f32 v[106:107], v[110:111], v[152:153], v[154:155]
	v_pk_fma_f32 v[154:155], v[94:95], v[152:153], v[156:157]
	v_pk_fma_f32 v[156:157], v[112:113], v[152:153], v[158:159]
	v_pk_fma_f32 v[158:159], v[96:97], v[152:153], v[160:161]
	v_pk_fma_f32 v[160:161], v[114:115], v[152:153], v[162:163]
	v_pk_fma_f32 v[162:163], v[98:99], v[152:153], v[164:165]
	v_pk_fma_f32 v[164:165], v[116:117], v[152:153], v[166:167]
	v_pk_fma_f32 v[166:167], v[100:101], v[152:153], v[168:169]
	v_pk_fma_f32 v[168:169], v[118:119], v[152:153], v[170:171]
	v_pk_fma_f32 v[170:171], v[102:103], v[152:153], v[172:173]
	v_pk_fma_f32 v[172:173], v[76:77], v[152:153], v[176:177]
	v_pk_fma_f32 v[176:177], v[130:131], v[152:153], v[178:179]
	v_pk_fma_f32 v[178:179], v[128:129], v[152:153], v[180:181]
	v_pk_fma_f32 v[150:151], v[126:127], v[152:153], v[150:151]
	v_lshlrev_b32_e32 v152, 16, v175
	v_and_b32_e32 v153, 0xffff0000, v175
	v_pk_fma_f32 v[90:91], v[92:93], v[152:153], v[90:91]
	v_pk_fma_f32 v[92:93], v[110:111], v[152:153], v[104:105]
	v_pk_fma_f32 v[104:105], v[94:95], v[152:153], v[106:107]
	v_pk_fma_f32 v[106:107], v[112:113], v[152:153], v[154:155]
	v_pk_fma_f32 v[154:155], v[96:97], v[152:153], v[156:157]
	v_pk_fma_f32 v[156:157], v[114:115], v[152:153], v[158:159]
	v_pk_fma_f32 v[158:159], v[98:99], v[152:153], v[160:161]
	v_pk_fma_f32 v[160:161], v[116:117], v[152:153], v[162:163]
	v_pk_fma_f32 v[162:163], v[100:101], v[152:153], v[164:165]
	v_pk_fma_f32 v[164:165], v[118:119], v[152:153], v[166:167]
	v_pk_fma_f32 v[166:167], v[102:103], v[152:153], v[168:169]
	v_pk_fma_f32 v[168:169], v[76:77], v[152:153], v[170:171]
	ds_read2st64_b32 v[170:171], v132 offset0:32 offset1:40
	v_pk_fma_f32 v[172:173], v[130:131], v[152:153], v[172:173]
	v_pk_fma_f32 v[174:175], v[128:129], v[152:153], v[176:177]
	v_pk_fma_f32 v[176:177], v[126:127], v[152:153], v[178:179]
	v_pk_fma_f32 v[150:151], v[124:125], v[152:153], v[150:151]
	s_waitcnt lgkmcnt(0)
	v_lshlrev_b32_e32 v152, 16, v170
	v_and_b32_e32 v153, 0xffff0000, v170
	v_pk_fma_f32 v[90:91], v[110:111], v[152:153], v[90:91]
	v_pk_fma_f32 v[92:93], v[94:95], v[152:153], v[92:93]
	v_pk_fma_f32 v[104:105], v[112:113], v[152:153], v[104:105]
	v_pk_fma_f32 v[106:107], v[96:97], v[152:153], v[106:107]
	v_pk_fma_f32 v[110:111], v[114:115], v[152:153], v[154:155]
	v_pk_fma_f32 v[154:155], v[98:99], v[152:153], v[156:157]
	v_pk_fma_f32 v[156:157], v[116:117], v[152:153], v[158:159]
	v_pk_fma_f32 v[158:159], v[100:101], v[152:153], v[160:161]
	v_pk_fma_f32 v[160:161], v[118:119], v[152:153], v[162:163]
	v_pk_fma_f32 v[162:163], v[102:103], v[152:153], v[164:165]
	v_pk_fma_f32 v[164:165], v[76:77], v[152:153], v[166:167]
	v_pk_fma_f32 v[166:167], v[130:131], v[152:153], v[168:169]
	v_pk_fma_f32 v[168:169], v[128:129], v[152:153], v[172:173]
	v_pk_fma_f32 v[172:173], v[126:127], v[152:153], v[174:175]
	v_pk_fma_f32 v[174:175], v[124:125], v[152:153], v[176:177]
	v_pk_fma_f32 v[150:151], v[122:123], v[152:153], v[150:151]
	v_lshlrev_b32_e32 v152, 16, v171
	v_and_b32_e32 v153, 0xffff0000, v171
	v_pk_fma_f32 v[90:91], v[94:95], v[152:153], v[90:91]
	v_pk_fma_f32 v[94:95], v[96:97], v[152:153], v[104:105]
	v_pk_fma_f32 v[104:105], v[114:115], v[152:153], v[106:107]
	v_pk_fma_f32 v[106:107], v[98:99], v[152:153], v[110:111]
	v_pk_fma_f32 v[110:111], v[116:117], v[152:153], v[154:155]
	v_pk_fma_f32 v[154:155], v[100:101], v[152:153], v[156:157]
	v_pk_fma_f32 v[156:157], v[118:119], v[152:153], v[158:159]
	v_pk_fma_f32 v[158:159], v[102:103], v[152:153], v[160:161]
	v_pk_fma_f32 v[160:161], v[76:77], v[152:153], v[162:163]
	v_pk_fma_f32 v[162:163], v[130:131], v[152:153], v[164:165]
	v_pk_fma_f32 v[164:165], v[128:129], v[152:153], v[166:167]
	ds_read2st64_b32 v[166:167], v132 offset0:48 offset1:56
	v_pk_fma_f32 v[92:93], v[112:113], v[152:153], v[92:93]
	v_pk_fma_f32 v[168:169], v[126:127], v[152:153], v[168:169]
	v_pk_fma_f32 v[170:171], v[124:125], v[152:153], v[172:173]
	v_pk_fma_f32 v[172:173], v[122:123], v[152:153], v[174:175]
	v_pk_fma_f32 v[150:151], v[120:121], v[152:153], v[150:151]
	s_waitcnt lgkmcnt(0)
; __device__ __forceinline__ float bf_lo(unsigned u) { return __uint_as_float(u << 16); }
; __device__ __forceinline__ float bf_hi(unsigned u) { return __uint_as_float(u & 0xffff0000u); }
; __device__ __forceinline__ void conv_run(LAS unsigned char* lds, const bf16_t* AG, bf16_t* CA, const float* cw, const float* cb, const float* lng, const float* lnb, int unit0, int nun, const int wave_s) {
;     ...
;         for (int j = 0; j < 31; ++j) { const unsigned wp = wl[j * 512 + tid]; const f32x2 w = (f32x2){bf_lo(wp), bf_hi(wp)};
; #pragma unroll
;             for (int t = 0; t < 16; ++t) acc[t] += w * in[t + j]; }
	v_lshlrev_b32_e32 v152, 16, v166
	v_and_b32_e32 v153, 0xffff0000, v166
	v_pk_fma_f32 v[90:91], v[112:113], v[152:153], v[90:91]
	v_pk_fma_f32 v[92:93], v[96:97], v[152:153], v[92:93]
	v_pk_fma_f32 v[94:95], v[114:115], v[152:153], v[94:95]
	v_pk_fma_f32 v[104:105], v[98:99], v[152:153], v[104:105]
	v_pk_fma_f32 v[106:107], v[116:117], v[152:153], v[106:107]
	v_pk_fma_f32 v[110:111], v[100:101], v[152:153], v[110:111]
	v_pk_fma_f32 v[112:113], v[118:119], v[152:153], v[154:155]
	v_pk_fma_f32 v[154:155], v[102:103], v[152:153], v[156:157]
	v_pk_fma_f32 v[156:157], v[76:77], v[152:153], v[158:159]
	v_pk_fma_f32 v[158:159], v[130:131], v[152:153], v[160:161]
	v_pk_fma_f32 v[160:161], v[128:129], v[152:153], v[162:163]
	v_pk_fma_f32 v[162:163], v[126:127], v[152:153], v[164:165]
	v_pk_fma_f32 v[164:165], v[124:125], v[152:153], v[168:169]
	v_pk_fma_f32 v[168:169], v[122:123], v[152:153], v[170:171]
	v_pk_fma_f32 v[170:171], v[120:121], v[152:153], v[172:173]
	v_pk_fma_f32 v[150:151], v[108:109], v[152:153], v[150:151]
	v_lshlrev_b32_e32 v152, 16, v167
	v_and_b32_e32 v153, 0xffff0000, v167
	v_pk_fma_f32 v[90:91], v[96:97], v[152:153], v[90:91]
	v_pk_fma_f32 v[96:97], v[116:117], v[152:153], v[104:105]
	v_pk_fma_f32 v[104:105], v[100:101], v[152:153], v[106:107]
	v_pk_fma_f32 v[106:107], v[118:119], v[152:153], v[110:111]
	v_pk_fma_f32 v[110:111], v[102:103], v[152:153], v[112:113]
	v_pk_fma_f32 v[112:113], v[76:77], v[152:153], v[154:155]
	v_pk_fma_f32 v[154:155], v[130:131], v[152:153], v[156:157]
	v_pk_fma_f32 v[156:157], v[128:129], v[152:153], v[158:159]
	v_pk_fma_f32 v[158:159], v[126:127], v[152:153], v[160:161]
	v_pk_fma_f32 v[160:161], v[124:125], v[152:153], v[162:163]
	ds_read2st64_b32 v[162:163], v132 offset0:64 offset1:72
	v_pk_fma_f32 v[92:93], v[114:115], v[152:153], v[92:93]
	v_pk_fma_f32 v[94:95], v[98:99], v[152:153], v[94:95]
	v_pk_fma_f32 v[164:165], v[122:123], v[152:153], v[164:165]
	v_pk_fma_f32 v[166:167], v[120:121], v[152:153], v[168:169]
	v_pk_fma_f32 v[168:169], v[108:109], v[152:153], v[170:171]
	v_pk_fma_f32 v[150:151], v[88:89], v[152:153], v[150:151]
	s_waitcnt lgkmcnt(0)
	v_lshlrev_b32_e32 v152, 16, v162
	v_and_b32_e32 v153, 0xffff0000, v162
	v_pk_fma_f32 v[90:91], v[114:115], v[152:153], v[90:91]
	v_pk_fma_f32 v[92:93], v[98:99], v[152:153], v[92:93]
	v_pk_fma_f32 v[94:95], v[116:117], v[152:153], v[94:95]
	v_pk_fma_f32 v[96:97], v[100:101], v[152:153], v[96:97]
	v_pk_fma_f32 v[104:105], v[118:119], v[152:153], v[104:105]
	v_pk_fma_f32 v[106:107], v[102:103], v[152:153], v[106:107]
	v_pk_fma_f32 v[110:111], v[76:77], v[152:153], v[110:111]
	v_pk_fma_f32 v[112:113], v[130:131], v[152:153], v[112:113]
	v_pk_fma_f32 v[114:115], v[128:129], v[152:153], v[154:155]
	v_pk_fma_f32 v[154:155], v[126:127], v[152:153], v[156:157]
	v_pk_fma_f32 v[156:157], v[124:125], v[152:153], v[158:159]
	v_pk_fma_f32 v[158:159], v[122:123], v[152:153], v[160:161]
	v_pk_fma_f32 v[160:161], v[120:121], v[152:153], v[164:165]
	v_pk_fma_f32 v[164:165], v[108:109], v[152:153], v[166:167]
	v_pk_fma_f32 v[166:167], v[88:89], v[152:153], v[168:169]
	v_pk_fma_f32 v[150:151], v[86:87], v[152:153], v[150:151]
	v_lshlrev_b32_e32 v152, 16, v163
	v_and_b32_e32 v153, 0xffff0000, v163
	v_pk_fma_f32 v[90:91], v[98:99], v[152:153], v[90:91]
	v_pk_fma_f32 v[98:99], v[102:103], v[152:153], v[104:105]
	v_pk_fma_f32 v[104:105], v[76:77], v[152:153], v[106:107]
	v_pk_fma_f32 v[106:107], v[130:131], v[152:153], v[110:111]
	v_pk_fma_f32 v[110:111], v[128:129], v[152:153], v[112:113]
	v_pk_fma_f32 v[112:113], v[126:127], v[152:153], v[114:115]
	v_pk_fma_f32 v[114:115], v[124:125], v[152:153], v[154:155]
	v_pk_fma_f32 v[154:155], v[122:123], v[152:153], v[156:157]
	v_pk_fma_f32 v[156:157], v[120:121], v[152:153], v[158:159]
	ds_read2st64_b32 v[158:159], v132 offset0:80 offset1:88
	v_pk_fma_f32 v[92:93], v[116:117], v[152:153], v[92:93]
	v_pk_fma_f32 v[94:95], v[100:101], v[152:153], v[94:95]
	v_pk_fma_f32 v[96:97], v[118:119], v[152:153], v[96:97]
	v_pk_fma_f32 v[160:161], v[108:109], v[152:153], v[160:161]
	v_pk_fma_f32 v[162:163], v[88:89], v[152:153], v[164:165]
	v_pk_fma_f32 v[164:165], v[86:87], v[152:153], v[166:167]
	v_pk_fma_f32 v[150:151], v[84:85], v[152:153], v[150:151]
	s_waitcnt lgkmcnt(0)
	v_lshlrev_b32_e32 v152, 16, v158
	v_and_b32_e32 v153, 0xffff0000, v158
	v_pk_fma_f32 v[90:91], v[116:117], v[152:153], v[90:91]
	v_pk_fma_f32 v[92:93], v[100:101], v[152:153], v[92:93]
	v_pk_fma_f32 v[94:95], v[118:119], v[152:153], v[94:95]
	v_pk_fma_f32 v[96:97], v[102:103], v[152:153], v[96:97]
	v_pk_fma_f32 v[98:99], v[76:77], v[152:153], v[98:99]
	v_pk_fma_f32 v[104:105], v[130:131], v[152:153], v[104:105]
	v_pk_fma_f32 v[106:107], v[128:129], v[152:153], v[106:107]
	v_pk_fma_f32 v[110:111], v[126:127], v[152:153], v[110:111]
	v_pk_fma_f32 v[112:113], v[124:125], v[152:153], v[112:113]
	v_pk_fma_f32 v[114:115], v[122:123], v[152:153], v[114:115]
	v_pk_fma_f32 v[116:117], v[120:121], v[152:153], v[154:155]
	v_pk_fma_f32 v[154:155], v[108:109], v[152:153], v[156:157]
	v_pk_fma_f32 v[156:157], v[88:89], v[152:153], v[160:161]
	v_pk_fma_f32 v[160:161], v[86:87], v[152:153], v[162:163]
	v_pk_fma_f32 v[162:163], v[84:85], v[152:153], v[164:165]
	v_pk_fma_f32 v[150:151], v[82:83], v[152:153], v[150:151]
	v_lshlrev_b32_e32 v152, 16, v159
	v_and_b32_e32 v153, 0xffff0000, v159
	v_pk_fma_f32 v[90:91], v[100:101], v[152:153], v[90:91]
	v_pk_fma_f32 v[100:101], v[128:129], v[152:153], v[104:105]
	v_pk_fma_f32 v[104:105], v[126:127], v[152:153], v[106:107]
	v_pk_fma_f32 v[106:107], v[124:125], v[152:153], v[110:111]
	v_pk_fma_f32 v[110:111], v[122:123], v[152:153], v[112:113]
	v_pk_fma_f32 v[112:113], v[120:121], v[152:153], v[114:115]
	v_pk_fma_f32 v[114:115], v[108:109], v[152:153], v[116:117]
	v_pk_fma_f32 v[116:117], v[88:89], v[152:153], v[154:155]
	ds_read2st64_b32 v[154:155], v132 offset0:96 offset1:104
	v_pk_fma_f32 v[92:93], v[118:119], v[152:153], v[92:93]
	v_pk_fma_f32 v[94:95], v[102:103], v[152:153], v[94:95]
	v_pk_fma_f32 v[96:97], v[76:77], v[152:153], v[96:97]
	v_pk_fma_f32 v[98:99], v[130:131], v[152:153], v[98:99]
	v_pk_fma_f32 v[156:157], v[86:87], v[152:153], v[156:157]
	v_pk_fma_f32 v[158:159], v[84:85], v[152:153], v[160:161]
	v_pk_fma_f32 v[160:161], v[82:83], v[152:153], v[162:163]
	v_pk_fma_f32 v[150:151], v[80:81], v[152:153], v[150:151]
	s_waitcnt lgkmcnt(0)
; __device__ __forceinline__ float bf_lo(unsigned u) { return __uint_as_float(u << 16); }
; __device__ __forceinline__ float bf_hi(unsigned u) { return __uint_as_float(u & 0xffff0000u); }
; __device__ __forceinline__ void conv_run(LAS unsigned char* lds, const bf16_t* AG, bf16_t* CA, const float* cw, const float* cb, const float* lng, const float* lnb, int unit0, int nun, const int wave_s) {
;     ...
;         for (int j = 0; j < 31; ++j) { const unsigned wp = wl[j * 512 + tid]; const f32x2 w = (f32x2){bf_lo(wp), bf_hi(wp)};
; #pragma unroll
;             for (int t = 0; t < 16; ++t) acc[t] += w * in[t + j]; }
	v_lshlrev_b32_e32 v152, 16, v154
	v_and_b32_e32 v153, 0xffff0000, v154
	v_pk_fma_f32 v[90:91], v[118:119], v[152:153], v[90:91]
	v_pk_fma_f32 v[92:93], v[102:103], v[152:153], v[92:93]
	v_pk_fma_f32 v[94:95], v[76:77], v[152:153], v[94:95]
	v_pk_fma_f32 v[96:97], v[130:131], v[152:153], v[96:97]
	v_pk_fma_f32 v[98:99], v[128:129], v[152:153], v[98:99]
	v_pk_fma_f32 v[100:101], v[126:127], v[152:153], v[100:101]
	v_pk_fma_f32 v[104:105], v[124:125], v[152:153], v[104:105]
	v_pk_fma_f32 v[106:107], v[122:123], v[152:153], v[106:107]
	v_pk_fma_f32 v[110:111], v[120:121], v[152:153], v[110:111]
	v_pk_fma_f32 v[112:113], v[108:109], v[152:153], v[112:113]
	v_pk_fma_f32 v[114:115], v[88:89], v[152:153], v[114:115]
	v_pk_fma_f32 v[116:117], v[86:87], v[152:153], v[116:117]
	v_pk_fma_f32 v[118:119], v[84:85], v[152:153], v[156:157]
	v_pk_fma_f32 v[156:157], v[82:83], v[152:153], v[158:159]
	v_pk_fma_f32 v[158:159], v[80:81], v[152:153], v[160:161]
	v_pk_fma_f32 v[150:151], v[78:79], v[152:153], v[150:151]
	v_lshlrev_b32_e32 v152, 16, v155
	v_and_b32_e32 v153, 0xffff0000, v155
	v_pk_fma_f32 v[90:91], v[102:103], v[152:153], v[90:91]
	v_pk_fma_f32 v[102:103], v[122:123], v[152:153], v[104:105]
	v_pk_fma_f32 v[104:105], v[120:121], v[152:153], v[106:107]
	v_pk_fma_f32 v[106:107], v[108:109], v[152:153], v[110:111]
	v_pk_fma_f32 v[110:111], v[88:89], v[152:153], v[112:113]
	v_pk_fma_f32 v[112:113], v[86:87], v[152:153], v[114:115]
	v_pk_fma_f32 v[114:115], v[84:85], v[152:153], v[116:117]
	ds_read2st64_b32 v[116:117], v132 offset0:112 offset1:120
	v_pk_fma_f32 v[92:93], v[76:77], v[152:153], v[92:93]
	v_pk_fma_f32 v[94:95], v[130:131], v[152:153], v[94:95]
	v_pk_fma_f32 v[96:97], v[128:129], v[152:153], v[96:97]
	v_pk_fma_f32 v[98:99], v[126:127], v[152:153], v[98:99]
	v_pk_fma_f32 v[100:101], v[124:125], v[152:153], v[100:101]
	v_pk_fma_f32 v[118:119], v[82:83], v[152:153], v[118:119]
	v_pk_fma_f32 v[154:155], v[80:81], v[152:153], v[156:157]
	v_pk_fma_f32 v[156:157], v[78:79], v[152:153], v[158:159]
	v_pk_fma_f32 v[150:151], v[74:75], v[152:153], v[150:151]
	s_waitcnt lgkmcnt(0)
	v_lshlrev_b32_e32 v152, 16, v116
	v_and_b32_e32 v153, 0xffff0000, v116
	v_pk_fma_f32 v[76:77], v[76:77], v[152:153], v[90:91]
	v_lshlrev_b32_e32 v116, 16, v117
	v_and_b32_e32 v117, 0xffff0000, v117
	v_pk_fma_f32 v[90:91], v[130:131], v[152:153], v[92:93]
	v_pk_fma_f32 v[76:77], v[130:131], v[116:117], v[76:77]
	ds_read2st64_b32 v[130:131], v132 offset0:128 offset1:136
	v_pk_fma_f32 v[92:93], v[128:129], v[152:153], v[94:95]
	v_pk_fma_f32 v[94:95], v[126:127], v[152:153], v[96:97]
	v_pk_fma_f32 v[96:97], v[124:125], v[152:153], v[98:99]
	v_pk_fma_f32 v[98:99], v[122:123], v[152:153], v[100:101]
	v_pk_fma_f32 v[100:101], v[120:121], v[152:153], v[102:103]
	v_pk_fma_f32 v[102:103], v[108:109], v[152:153], v[104:105]
	v_pk_fma_f32 v[104:105], v[88:89], v[152:153], v[106:107]
	v_pk_fma_f32 v[106:107], v[86:87], v[152:153], v[110:111]
	v_pk_fma_f32 v[110:111], v[84:85], v[152:153], v[112:113]
	v_pk_fma_f32 v[112:113], v[82:83], v[152:153], v[114:115]
	v_pk_fma_f32 v[114:115], v[80:81], v[152:153], v[118:119]
	v_pk_fma_f32 v[118:119], v[78:79], v[152:153], v[154:155]
	v_pk_fma_f32 v[154:155], v[74:75], v[152:153], v[156:157]
	v_pk_fma_f32 v[150:151], v[72:73], v[152:153], v[150:151]
	v_pk_fma_f32 v[90:91], v[128:129], v[116:117], v[90:91]
	v_pk_fma_f32 v[92:93], v[126:127], v[116:117], v[92:93]
	v_pk_fma_f32 v[94:95], v[124:125], v[116:117], v[94:95]
	v_pk_fma_f32 v[96:97], v[122:123], v[116:117], v[96:97]
	v_pk_fma_f32 v[98:99], v[120:121], v[116:117], v[98:99]
	v_pk_fma_f32 v[100:101], v[108:109], v[116:117], v[100:101]
	v_pk_fma_f32 v[102:103], v[88:89], v[116:117], v[102:103]
	v_pk_fma_f32 v[104:105], v[86:87], v[116:117], v[104:105]
	v_pk_fma_f32 v[106:107], v[84:85], v[116:117], v[106:107]
	v_pk_fma_f32 v[110:111], v[82:83], v[116:117], v[110:111]
	v_pk_fma_f32 v[112:113], v[80:81], v[116:117], v[112:113]
	v_pk_fma_f32 v[114:115], v[78:79], v[116:117], v[114:115]
	v_pk_fma_f32 v[118:119], v[74:75], v[116:117], v[118:119]
	v_pk_fma_f32 v[152:153], v[72:73], v[116:117], v[154:155]
	v_pk_fma_f32 v[116:117], v[26:27], v[116:117], v[150:151]
	s_waitcnt lgkmcnt(0)
	v_lshlrev_b32_e32 v150, 16, v130
	v_and_b32_e32 v151, 0xffff0000, v130
	v_pk_fma_f32 v[76:77], v[128:129], v[150:151], v[76:77]
	v_lshlrev_b32_e32 v130, 16, v131
	v_and_b32_e32 v131, 0xffff0000, v131
	v_pk_fma_f32 v[90:91], v[126:127], v[150:151], v[90:91]
	v_pk_fma_f32 v[76:77], v[126:127], v[130:131], v[76:77]
	ds_read2st64_b32 v[126:127], v132 offset0:144 offset1:152
	v_pk_fma_f32 v[92:93], v[124:125], v[150:151], v[92:93]
	v_pk_fma_f32 v[94:95], v[122:123], v[150:151], v[94:95]
	v_pk_fma_f32 v[96:97], v[120:121], v[150:151], v[96:97]
	v_pk_fma_f32 v[98:99], v[108:109], v[150:151], v[98:99]
	v_pk_fma_f32 v[100:101], v[88:89], v[150:151], v[100:101]
	v_pk_fma_f32 v[102:103], v[86:87], v[150:151], v[102:103]
	v_pk_fma_f32 v[104:105], v[84:85], v[150:151], v[104:105]
	v_pk_fma_f32 v[106:107], v[82:83], v[150:151], v[106:107]
	v_pk_fma_f32 v[110:111], v[80:81], v[150:151], v[110:111]
	v_pk_fma_f32 v[112:113], v[78:79], v[150:151], v[112:113]
	v_pk_fma_f32 v[114:115], v[74:75], v[150:151], v[114:115]
	v_pk_fma_f32 v[118:119], v[72:73], v[150:151], v[118:119]
	v_pk_fma_f32 v[128:129], v[26:27], v[150:151], v[152:153]
	v_pk_fma_f32 v[116:117], v[12:13], v[150:151], v[116:117]
	v_pk_fma_f32 v[90:91], v[124:125], v[130:131], v[90:91]
	v_pk_fma_f32 v[92:93], v[122:123], v[130:131], v[92:93]
	v_pk_fma_f32 v[94:95], v[120:121], v[130:131], v[94:95]
	v_pk_fma_f32 v[96:97], v[108:109], v[130:131], v[96:97]
	v_pk_fma_f32 v[98:99], v[88:89], v[130:131], v[98:99]
	v_pk_fma_f32 v[100:101], v[86:87], v[130:131], v[100:101]
	v_pk_fma_f32 v[102:103], v[84:85], v[130:131], v[102:103]
	v_pk_fma_f32 v[104:105], v[82:83], v[130:131], v[104:105]
	v_pk_fma_f32 v[106:107], v[80:81], v[130:131], v[106:107]
	v_pk_fma_f32 v[110:111], v[78:79], v[130:131], v[110:111]
	v_pk_fma_f32 v[112:113], v[74:75], v[130:131], v[112:113]
	v_pk_fma_f32 v[114:115], v[72:73], v[130:131], v[114:115]
	v_pk_fma_f32 v[118:119], v[26:27], v[130:131], v[118:119]
	v_pk_fma_f32 v[128:129], v[12:13], v[130:131], v[128:129]
	v_pk_fma_f32 v[116:117], v[14:15], v[130:131], v[116:117]
	s_waitcnt lgkmcnt(0)
; __device__ __forceinline__ float bf_lo(unsigned u) { return __uint_as_float(u << 16); }
; __device__ __forceinline__ float bf_hi(unsigned u) { return __uint_as_float(u & 0xffff0000u); }
; __device__ __forceinline__ void conv_run(LAS unsigned char* lds, const bf16_t* AG, bf16_t* CA, const float* cw, const float* cb, const float* lng, const float* lnb, int unit0, int nun, const int wave_s) {
;     ...
;         for (int j = 0; j < 31; ++j) { const unsigned wp = wl[j * 512 + tid]; const f32x2 w = (f32x2){bf_lo(wp), bf_hi(wp)};
; #pragma unroll
;             for (int t = 0; t < 16; ++t) acc[t] += w * in[t + j]; }
	v_lshlrev_b32_e32 v130, 16, v126
	v_and_b32_e32 v131, 0xffff0000, v126
	v_pk_fma_f32 v[76:77], v[124:125], v[130:131], v[76:77]
	v_lshlrev_b32_e32 v126, 16, v127
	v_and_b32_e32 v127, 0xffff0000, v127
	v_pk_fma_f32 v[90:91], v[122:123], v[130:131], v[90:91]
	v_pk_fma_f32 v[76:77], v[122:123], v[126:127], v[76:77]
	ds_read2st64_b32 v[122:123], v132 offset0:160 offset1:168
	v_pk_fma_f32 v[92:93], v[120:121], v[130:131], v[92:93]
	v_pk_fma_f32 v[94:95], v[108:109], v[130:131], v[94:95]
	v_pk_fma_f32 v[96:97], v[88:89], v[130:131], v[96:97]
	v_pk_fma_f32 v[98:99], v[86:87], v[130:131], v[98:99]
	v_pk_fma_f32 v[100:101], v[84:85], v[130:131], v[100:101]
	v_pk_fma_f32 v[102:103], v[82:83], v[130:131], v[102:103]
	v_pk_fma_f32 v[104:105], v[80:81], v[130:131], v[104:105]
	v_pk_fma_f32 v[106:107], v[78:79], v[130:131], v[106:107]
	v_pk_fma_f32 v[110:111], v[74:75], v[130:131], v[110:111]
	v_pk_fma_f32 v[112:113], v[72:73], v[130:131], v[112:113]
	v_pk_fma_f32 v[114:115], v[26:27], v[130:131], v[114:115]
	v_pk_fma_f32 v[118:119], v[12:13], v[130:131], v[118:119]
	v_pk_fma_f32 v[124:125], v[14:15], v[130:131], v[128:129]
	v_pk_fma_f32 v[116:117], v[16:17], v[130:131], v[116:117]
	v_pk_fma_f32 v[90:91], v[120:121], v[126:127], v[90:91]
	v_pk_fma_f32 v[92:93], v[108:109], v[126:127], v[92:93]
	v_pk_fma_f32 v[94:95], v[88:89], v[126:127], v[94:95]
	v_pk_fma_f32 v[96:97], v[86:87], v[126:127], v[96:97]
	v_pk_fma_f32 v[98:99], v[84:85], v[126:127], v[98:99]
	v_pk_fma_f32 v[100:101], v[82:83], v[126:127], v[100:101]
	v_pk_fma_f32 v[102:103], v[80:81], v[126:127], v[102:103]
	v_pk_fma_f32 v[104:105], v[78:79], v[126:127], v[104:105]
	v_pk_fma_f32 v[106:107], v[74:75], v[126:127], v[106:107]
	v_pk_fma_f32 v[110:111], v[72:73], v[126:127], v[110:111]
	v_pk_fma_f32 v[112:113], v[26:27], v[126:127], v[112:113]
	v_pk_fma_f32 v[114:115], v[12:13], v[126:127], v[114:115]
	v_pk_fma_f32 v[118:119], v[14:15], v[126:127], v[118:119]
	v_pk_fma_f32 v[124:125], v[16:17], v[126:127], v[124:125]
	v_pk_fma_f32 v[116:117], v[18:19], v[126:127], v[116:117]
	s_waitcnt lgkmcnt(0)
	v_lshlrev_b32_e32 v126, 16, v122
	v_and_b32_e32 v127, 0xffff0000, v122
	v_pk_fma_f32 v[76:77], v[120:121], v[126:127], v[76:77]
	v_pk_fma_f32 v[110:111], v[26:27], v[126:127], v[110:111]
	v_pk_fma_f32 v[112:113], v[12:13], v[126:127], v[112:113]
	v_lshlrev_b32_e32 v122, 16, v123
	v_and_b32_e32 v123, 0xffff0000, v123
	v_pk_fma_f32 v[90:91], v[108:109], v[126:127], v[90:91]
	v_pk_fma_f32 v[76:77], v[108:109], v[122:123], v[76:77]
	v_pk_fma_f32 v[108:109], v[12:13], v[122:123], v[110:111]
	v_pk_fma_f32 v[110:111], v[14:15], v[122:123], v[112:113]
	ds_read2st64_b32 v[112:113], v132 offset0:176 offset1:184
	v_pk_fma_f32 v[92:93], v[88:89], v[126:127], v[92:93]
	v_pk_fma_f32 v[94:95], v[86:87], v[126:127], v[94:95]
	v_pk_fma_f32 v[96:97], v[84:85], v[126:127], v[96:97]
	v_pk_fma_f32 v[98:99], v[82:83], v[126:127], v[98:99]
	v_pk_fma_f32 v[100:101], v[80:81], v[126:127], v[100:101]
	v_pk_fma_f32 v[102:103], v[78:79], v[126:127], v[102:103]
	v_pk_fma_f32 v[104:105], v[74:75], v[126:127], v[104:105]
	v_pk_fma_f32 v[106:107], v[72:73], v[126:127], v[106:107]
	v_pk_fma_f32 v[114:115], v[14:15], v[126:127], v[114:115]
	v_pk_fma_f32 v[118:119], v[16:17], v[126:127], v[118:119]
	v_pk_fma_f32 v[120:121], v[18:19], v[126:127], v[124:125]
	v_pk_fma_f32 v[116:117], v[20:21], v[126:127], v[116:117]
	v_pk_fma_f32 v[90:91], v[88:89], v[122:123], v[90:91]
	v_pk_fma_f32 v[92:93], v[86:87], v[122:123], v[92:93]
	v_pk_fma_f32 v[94:95], v[84:85], v[122:123], v[94:95]
	v_pk_fma_f32 v[96:97], v[82:83], v[122:123], v[96:97]
	v_pk_fma_f32 v[98:99], v[80:81], v[122:123], v[98:99]
	v_pk_fma_f32 v[100:101], v[78:79], v[122:123], v[100:101]
	v_pk_fma_f32 v[102:103], v[74:75], v[122:123], v[102:103]
	v_pk_fma_f32 v[104:105], v[72:73], v[122:123], v[104:105]
	v_pk_fma_f32 v[106:107], v[26:27], v[122:123], v[106:107]
	v_pk_fma_f32 v[114:115], v[16:17], v[122:123], v[114:115]
	v_pk_fma_f32 v[118:119], v[18:19], v[122:123], v[118:119]
	v_pk_fma_f32 v[120:121], v[20:21], v[122:123], v[120:121]
	v_pk_fma_f32 v[116:117], v[22:23], v[122:123], v[116:117]
	s_waitcnt lgkmcnt(0)
	v_lshlrev_b32_e32 v122, 16, v112
	v_and_b32_e32 v123, 0xffff0000, v112
	v_pk_fma_f32 v[76:77], v[88:89], v[122:123], v[76:77]
	v_pk_fma_f32 v[88:89], v[86:87], v[122:123], v[90:91]
	v_pk_fma_f32 v[90:91], v[84:85], v[122:123], v[92:93]
	v_pk_fma_f32 v[92:93], v[82:83], v[122:123], v[94:95]
	v_pk_fma_f32 v[94:95], v[80:81], v[122:123], v[96:97]
	v_pk_fma_f32 v[96:97], v[78:79], v[122:123], v[98:99]
	v_pk_fma_f32 v[98:99], v[74:75], v[122:123], v[100:101]
	v_pk_fma_f32 v[100:101], v[72:73], v[122:123], v[102:103]
	v_pk_fma_f32 v[102:103], v[26:27], v[122:123], v[104:105]
	v_pk_fma_f32 v[104:105], v[12:13], v[122:123], v[106:107]
	v_pk_fma_f32 v[106:107], v[14:15], v[122:123], v[108:109]
	v_pk_fma_f32 v[108:109], v[16:17], v[122:123], v[110:111]
	v_lshlrev_b32_e32 v112, 16, v113
	v_and_b32_e32 v113, 0xffff0000, v113
	v_pk_fma_f32 v[76:77], v[86:87], v[112:113], v[76:77]
	v_pk_fma_f32 v[86:87], v[84:85], v[112:113], v[88:89]
	v_pk_fma_f32 v[88:89], v[82:83], v[112:113], v[90:91]
	v_pk_fma_f32 v[90:91], v[80:81], v[112:113], v[92:93]
	v_pk_fma_f32 v[92:93], v[78:79], v[112:113], v[94:95]
	v_pk_fma_f32 v[94:95], v[74:75], v[112:113], v[96:97]
	v_pk_fma_f32 v[96:97], v[72:73], v[112:113], v[98:99]
	v_pk_fma_f32 v[98:99], v[26:27], v[112:113], v[100:101]
	v_pk_fma_f32 v[100:101], v[12:13], v[112:113], v[102:103]
	v_pk_fma_f32 v[102:103], v[14:15], v[112:113], v[104:105]
	v_pk_fma_f32 v[104:105], v[16:17], v[112:113], v[106:107]
	v_pk_fma_f32 v[106:107], v[18:19], v[112:113], v[108:109]
	ds_read2st64_b32 v[108:109], v132 offset0:192 offset1:200
	v_pk_fma_f32 v[110:111], v[18:19], v[122:123], v[114:115]
	v_pk_fma_f32 v[114:115], v[20:21], v[122:123], v[118:119]
	v_pk_fma_f32 v[118:119], v[22:23], v[122:123], v[120:121]
	v_pk_fma_f32 v[116:117], v[24:25], v[122:123], v[116:117]
	v_pk_fma_f32 v[110:111], v[20:21], v[112:113], v[110:111]
	v_pk_fma_f32 v[114:115], v[22:23], v[112:113], v[114:115]
	v_pk_fma_f32 v[118:119], v[24:25], v[112:113], v[118:119]
	v_pk_fma_f32 v[112:113], v[28:29], v[112:113], v[116:117]
	s_waitcnt lgkmcnt(0)
; __device__ __forceinline__ float bf_lo(unsigned u) { return __uint_as_float(u << 16); }
; __device__ __forceinline__ float bf_hi(unsigned u) { return __uint_as_float(u & 0xffff0000u); }
; __device__ __forceinline__ void conv_run(LAS unsigned char* lds, const bf16_t* AG, bf16_t* CA, const float* cw, const float* cb, const float* lng, const float* lnb, int unit0, int nun, const int wave_s) {
;     ...
;         for (int j = 0; j < 31; ++j) { const unsigned wp = wl[j * 512 + tid]; const f32x2 w = (f32x2){bf_lo(wp), bf_hi(wp)};
; #pragma unroll
;             for (int t = 0; t < 16; ++t) acc[t] += w * in[t + j]; }
	v_lshlrev_b32_e32 v116, 16, v108
	v_and_b32_e32 v117, 0xffff0000, v108
	v_pk_fma_f32 v[76:77], v[84:85], v[116:117], v[76:77]
	v_pk_fma_f32 v[84:85], v[82:83], v[116:117], v[86:87]
	v_pk_fma_f32 v[86:87], v[80:81], v[116:117], v[88:89]
	v_pk_fma_f32 v[88:89], v[78:79], v[116:117], v[90:91]
	v_pk_fma_f32 v[90:91], v[74:75], v[116:117], v[92:93]
	v_pk_fma_f32 v[92:93], v[72:73], v[116:117], v[94:95]
	v_pk_fma_f32 v[94:95], v[26:27], v[116:117], v[96:97]
	v_pk_fma_f32 v[96:97], v[12:13], v[116:117], v[98:99]
	v_pk_fma_f32 v[98:99], v[14:15], v[116:117], v[100:101]
	v_pk_fma_f32 v[100:101], v[16:17], v[116:117], v[102:103]
	v_pk_fma_f32 v[102:103], v[18:19], v[116:117], v[104:105]
	v_pk_fma_f32 v[104:105], v[20:21], v[116:117], v[106:107]
	v_lshlrev_b32_e32 v108, 16, v109
	v_and_b32_e32 v109, 0xffff0000, v109
	v_pk_fma_f32 v[76:77], v[82:83], v[108:109], v[76:77]
	v_pk_fma_f32 v[82:83], v[80:81], v[108:109], v[84:85]
	v_pk_fma_f32 v[84:85], v[78:79], v[108:109], v[86:87]
	v_pk_fma_f32 v[86:87], v[74:75], v[108:109], v[88:89]
	v_pk_fma_f32 v[88:89], v[72:73], v[108:109], v[90:91]
	v_pk_fma_f32 v[90:91], v[26:27], v[108:109], v[92:93]
	v_pk_fma_f32 v[92:93], v[12:13], v[108:109], v[94:95]
	v_pk_fma_f32 v[94:95], v[14:15], v[108:109], v[96:97]
	v_pk_fma_f32 v[96:97], v[16:17], v[108:109], v[98:99]
	v_pk_fma_f32 v[98:99], v[18:19], v[108:109], v[100:101]
	v_pk_fma_f32 v[100:101], v[20:21], v[108:109], v[102:103]
	v_pk_fma_f32 v[102:103], v[22:23], v[108:109], v[104:105]
	ds_read2st64_b32 v[104:105], v132 offset0:208 offset1:216
	v_pk_fma_f32 v[106:107], v[22:23], v[116:117], v[110:111]
	v_pk_fma_f32 v[110:111], v[24:25], v[116:117], v[114:115]
	v_pk_fma_f32 v[114:115], v[28:29], v[116:117], v[118:119]
	v_pk_fma_f32 v[112:113], v[30:31], v[116:117], v[112:113]
	v_pk_fma_f32 v[106:107], v[24:25], v[108:109], v[106:107]
	v_pk_fma_f32 v[110:111], v[28:29], v[108:109], v[110:111]
	v_pk_fma_f32 v[114:115], v[30:31], v[108:109], v[114:115]
	v_pk_fma_f32 v[108:109], v[32:33], v[108:109], v[112:113]
	s_waitcnt lgkmcnt(0)
	v_lshlrev_b32_e32 v112, 16, v104
	v_and_b32_e32 v113, 0xffff0000, v104
	v_pk_fma_f32 v[76:77], v[80:81], v[112:113], v[76:77]
	v_pk_fma_f32 v[80:81], v[78:79], v[112:113], v[82:83]
	v_pk_fma_f32 v[82:83], v[74:75], v[112:113], v[84:85]
	v_pk_fma_f32 v[84:85], v[72:73], v[112:113], v[86:87]
	v_pk_fma_f32 v[86:87], v[26:27], v[112:113], v[88:89]
	v_pk_fma_f32 v[88:89], v[12:13], v[112:113], v[90:91]
	v_pk_fma_f32 v[90:91], v[14:15], v[112:113], v[92:93]
	v_pk_fma_f32 v[92:93], v[16:17], v[112:113], v[94:95]
	v_pk_fma_f32 v[94:95], v[18:19], v[112:113], v[96:97]
	v_pk_fma_f32 v[96:97], v[20:21], v[112:113], v[98:99]
	v_pk_fma_f32 v[98:99], v[22:23], v[112:113], v[100:101]
	v_pk_fma_f32 v[100:101], v[24:25], v[112:113], v[102:103]
	v_lshlrev_b32_e32 v104, 16, v105
	v_and_b32_e32 v105, 0xffff0000, v105
	v_pk_fma_f32 v[76:77], v[78:79], v[104:105], v[76:77]
	v_pk_fma_f32 v[78:79], v[74:75], v[104:105], v[80:81]
	v_pk_fma_f32 v[80:81], v[72:73], v[104:105], v[82:83]
	v_pk_fma_f32 v[82:83], v[26:27], v[104:105], v[84:85]
	v_pk_fma_f32 v[84:85], v[12:13], v[104:105], v[86:87]
	v_pk_fma_f32 v[86:87], v[14:15], v[104:105], v[88:89]
	v_pk_fma_f32 v[88:89], v[16:17], v[104:105], v[90:91]
	v_pk_fma_f32 v[90:91], v[18:19], v[104:105], v[92:93]
	v_pk_fma_f32 v[92:93], v[20:21], v[104:105], v[94:95]
	v_pk_fma_f32 v[94:95], v[22:23], v[104:105], v[96:97]
	v_pk_fma_f32 v[96:97], v[24:25], v[104:105], v[98:99]
	v_pk_fma_f32 v[98:99], v[28:29], v[104:105], v[100:101]
	ds_read2st64_b32 v[100:101], v132 offset0:224 offset1:232
	v_pk_fma_f32 v[102:103], v[28:29], v[112:113], v[106:107]
	v_pk_fma_f32 v[106:107], v[30:31], v[112:113], v[110:111]
	v_pk_fma_f32 v[110:111], v[32:33], v[112:113], v[114:115]
	v_pk_fma_f32 v[108:109], v[34:35], v[112:113], v[108:109]
	v_pk_fma_f32 v[102:103], v[30:31], v[104:105], v[102:103]
	v_pk_fma_f32 v[106:107], v[32:33], v[104:105], v[106:107]
	v_pk_fma_f32 v[110:111], v[34:35], v[104:105], v[110:111]
	v_pk_fma_f32 v[104:105], v[36:37], v[104:105], v[108:109]
	s_waitcnt lgkmcnt(0)
	v_lshlrev_b32_e32 v108, 16, v100
	v_and_b32_e32 v109, 0xffff0000, v100
	v_pk_fma_f32 v[74:75], v[74:75], v[108:109], v[76:77]
	v_pk_fma_f32 v[76:77], v[72:73], v[108:109], v[78:79]
	v_pk_fma_f32 v[78:79], v[26:27], v[108:109], v[80:81]
	v_pk_fma_f32 v[80:81], v[12:13], v[108:109], v[82:83]
	v_pk_fma_f32 v[82:83], v[14:15], v[108:109], v[84:85]
	v_pk_fma_f32 v[84:85], v[16:17], v[108:109], v[86:87]
	v_pk_fma_f32 v[86:87], v[18:19], v[108:109], v[88:89]
	v_pk_fma_f32 v[88:89], v[20:21], v[108:109], v[90:91]
	v_lshlrev_b32_e32 v100, 16, v101
	v_and_b32_e32 v101, 0xffff0000, v101
	v_pk_fma_f32 v[72:73], v[72:73], v[100:101], v[74:75]
	v_pk_fma_f32 v[74:75], v[26:27], v[100:101], v[76:77]
	v_pk_fma_f32 v[76:77], v[12:13], v[100:101], v[78:79]
	v_pk_fma_f32 v[78:79], v[14:15], v[100:101], v[80:81]
	v_pk_fma_f32 v[80:81], v[16:17], v[100:101], v[82:83]
	v_pk_fma_f32 v[82:83], v[18:19], v[100:101], v[84:85]
	v_pk_fma_f32 v[84:85], v[20:21], v[100:101], v[86:87]
	v_pk_fma_f32 v[86:87], v[22:23], v[100:101], v[88:89]
	ds_read_b32 v88, v132 offset:61440
	v_pk_fma_f32 v[90:91], v[22:23], v[108:109], v[92:93]
	v_pk_fma_f32 v[92:93], v[24:25], v[108:109], v[94:95]
	v_pk_fma_f32 v[94:95], v[28:29], v[108:109], v[96:97]
	v_pk_fma_f32 v[96:97], v[30:31], v[108:109], v[98:99]
	v_pk_fma_f32 v[98:99], v[32:33], v[108:109], v[102:103]
	v_pk_fma_f32 v[102:103], v[34:35], v[108:109], v[106:107]
	v_pk_fma_f32 v[104:105], v[38:39], v[108:109], v[104:105]
	s_waitcnt lgkmcnt(0)
; __device__ __forceinline__ float bf_lo(unsigned u) { return __uint_as_float(u << 16); }
; __device__ __forceinline__ float bf_hi(unsigned u) { return __uint_as_float(u & 0xffff0000u); }
; __device__ __forceinline__ void conv_run(LAS unsigned char* lds, const bf16_t* AG, bf16_t* CA, const float* cw, const float* cb, const float* lng, const float* lnb, int unit0, int nun, const int wave_s) {
;     ...
;         for (int j = 0; j < 31; ++j) { const unsigned wp = wl[j * 512 + tid]; const f32x2 w = (f32x2){bf_lo(wp), bf_hi(wp)};
; #pragma unroll
;             for (int t = 0; t < 16; ++t) acc[t] += w * in[t + j]; }
; #pragma unroll
;         for (int t = 0; t < 16; ++t) { red[(2 * t) * 512 + tid] = acc[t].x + acc[t].y; red[(2 * t + 1) * 512 + tid] = acc[t].x * acc[t].x + acc[t].y * acc[t].y; }
;         __syncthreads();
	v_lshlrev_b32_e32 v120, 16, v88
	v_and_b32_e32 v121, 0xffff0000, v88
	v_pk_fma_f32 v[106:107], v[36:37], v[108:109], v[110:111]
	v_pk_fma_f32 v[118:119], v[36:37], v[100:101], v[102:103]
	v_pk_fma_f32 v[104:105], v[40:41], v[100:101], v[104:105]
	v_pk_fma_f32 v[102:103], v[26:27], v[120:121], v[72:73]
	v_pk_fma_f32 v[106:107], v[38:39], v[100:101], v[106:107]
	v_pk_fma_f32 v[72:73], v[42:43], v[120:121], v[104:105]
	v_pk_mul_f32 v[104:105], v[102:103], v[102:103]
	v_pk_fma_f32 v[108:109], v[24:25], v[100:101], v[90:91]
	v_pk_fma_f32 v[110:111], v[28:29], v[100:101], v[92:93]
	v_pk_fma_f32 v[112:113], v[30:31], v[100:101], v[94:95]
	v_pk_fma_f32 v[114:115], v[32:33], v[100:101], v[96:97]
	v_pk_fma_f32 v[116:117], v[34:35], v[100:101], v[98:99]
	v_pk_fma_f32 v[100:101], v[12:13], v[120:121], v[74:75]
	v_pk_fma_f32 v[74:75], v[40:41], v[120:121], v[106:107]
	v_add_f32_e32 v106, v102, v103
	v_add_f32_e32 v104, v104, v105
	ds_write2st64_b32 v0, v106, v104 offset1:8
	v_pk_mul_f32 v[104:105], v[100:101], v[100:101]
	v_pk_fma_f32 v[98:99], v[14:15], v[120:121], v[76:77]
	v_add_f32_e32 v106, v100, v101
	v_add_f32_e32 v104, v104, v105
	ds_write2st64_b32 v0, v106, v104 offset0:16 offset1:24
	v_pk_mul_f32 v[104:105], v[98:99], v[98:99]
	v_pk_fma_f32 v[96:97], v[16:17], v[120:121], v[78:79]
	v_add_f32_e32 v106, v98, v99
	v_add_f32_e32 v104, v104, v105
	ds_write2st64_b32 v0, v106, v104 offset0:32 offset1:40
	v_pk_mul_f32 v[104:105], v[96:97], v[96:97]
	v_pk_fma_f32 v[94:95], v[18:19], v[120:121], v[80:81]
	v_add_f32_e32 v106, v96, v97
	v_add_f32_e32 v104, v104, v105
	ds_write2st64_b32 v0, v106, v104 offset0:48 offset1:56
	v_pk_mul_f32 v[104:105], v[94:95], v[94:95]
	v_pk_fma_f32 v[92:93], v[20:21], v[120:121], v[82:83]
	v_add_f32_e32 v106, v94, v95
	v_add_f32_e32 v104, v104, v105
	ds_write2st64_b32 v0, v106, v104 offset0:64 offset1:72
	v_pk_mul_f32 v[104:105], v[92:93], v[92:93]
	v_pk_fma_f32 v[90:91], v[22:23], v[120:121], v[84:85]
	v_add_f32_e32 v106, v92, v93
	v_add_f32_e32 v104, v104, v105
	ds_write2st64_b32 v0, v106, v104 offset0:80 offset1:88
	v_pk_mul_f32 v[104:105], v[90:91], v[90:91]
	v_pk_fma_f32 v[88:89], v[24:25], v[120:121], v[86:87]
	v_add_f32_e32 v106, v90, v91
	v_add_f32_e32 v104, v104, v105
	ds_write2st64_b32 v0, v106, v104 offset0:96 offset1:104
	v_pk_mul_f32 v[104:105], v[88:89], v[88:89]
	v_pk_fma_f32 v[86:87], v[28:29], v[120:121], v[108:109]
	v_add_f32_e32 v106, v88, v89
	v_add_f32_e32 v104, v104, v105
	ds_write2st64_b32 v0, v106, v104 offset0:112 offset1:120
	v_pk_mul_f32 v[104:105], v[86:87], v[86:87]
	v_pk_fma_f32 v[84:85], v[30:31], v[120:121], v[110:111]
	v_add_f32_e32 v106, v86, v87
	v_add_f32_e32 v104, v104, v105
	ds_write2st64_b32 v0, v106, v104 offset0:128 offset1:136
	v_pk_mul_f32 v[104:105], v[84:85], v[84:85]
	v_pk_fma_f32 v[82:83], v[32:33], v[120:121], v[112:113]
	v_add_f32_e32 v106, v84, v85
	v_add_f32_e32 v104, v104, v105
	ds_write2st64_b32 v0, v106, v104 offset0:144 offset1:152
	v_pk_mul_f32 v[104:105], v[82:83], v[82:83]
	v_pk_fma_f32 v[80:81], v[34:35], v[120:121], v[114:115]
	v_add_f32_e32 v106, v82, v83
	v_add_f32_e32 v104, v104, v105
	ds_write2st64_b32 v0, v106, v104 offset0:160 offset1:168
	v_pk_mul_f32 v[104:105], v[80:81], v[80:81]
	v_pk_fma_f32 v[78:79], v[36:37], v[120:121], v[116:117]
	v_add_f32_e32 v106, v80, v81
	v_add_f32_e32 v104, v104, v105
	ds_write2st64_b32 v0, v106, v104 offset0:176 offset1:184
	v_pk_mul_f32 v[104:105], v[78:79], v[78:79]
	v_pk_fma_f32 v[76:77], v[38:39], v[120:121], v[118:119]
	v_add_f32_e32 v106, v78, v79
	v_add_f32_e32 v104, v104, v105
	ds_write2st64_b32 v0, v106, v104 offset0:192 offset1:200
	v_pk_mul_f32 v[104:105], v[76:77], v[76:77]
	v_add_f32_e32 v106, v76, v77
	v_add_f32_e32 v104, v104, v105
	ds_write2st64_b32 v0, v106, v104 offset0:208 offset1:216
	v_pk_mul_f32 v[104:105], v[74:75], v[74:75]
	v_add_f32_e32 v106, v74, v75
	v_add_f32_e32 v104, v104, v105
	ds_write2st64_b32 v0, v106, v104 offset0:224 offset1:232
	v_pk_mul_f32 v[104:105], v[72:73], v[72:73]
	v_add_f32_e32 v106, v72, v73
	v_add_f32_e32 v104, v104, v105
	v_add_u32_e32 v118, s13, v133
	ds_write2st64_b32 v0, v106, v104 offset0:240 offset1:248
	s_waitcnt lgkmcnt(0)
	s_barrier
; __device__ __forceinline__ void conv_run(LAS unsigned char* lds, const bf16_t* AG, bf16_t* CA, const float* cw, const float* cb, const float* lng, const float* lnb, int unit0, int nun, const int wave_s) {
;     ...
;         for (int r = 0; r < 2; ++r) { const int tk = wid * 2 + r; float sm = 0.f, sq = 0.f;
; #pragma unroll
;             for (int i = 0; i < 8; ++i) { sm += red[(2 * tk) * 512 + lane + 64 * i]; sq += red[(2 * tk + 1) * 512 + lane + 64 * i]; }
;             sm = wave_sum(sm); sq = wave_sum(sq);
;             if (lane == 0) { const float mean = sm * (1.f / DM), var = sq * (1.f / DM) - mean * mean; stat[2 * tk] = mean; stat[2 * tk + 1] = __builtin_amdgcn_rsqf(var + EPS); } }
	ds_read2st64_b32 v[104:105], v118 offset1:1
	ds_read2st64_b32 v[106:107], v118 offset0:8 offset1:9
	ds_read2st64_b32 v[108:109], v118 offset0:2 offset1:3
	ds_read2st64_b32 v[110:111], v118 offset0:4 offset1:5
	ds_read2st64_b32 v[112:113], v118 offset0:6 offset1:7
	ds_read2st64_b32 v[114:115], v118 offset0:10 offset1:11
	ds_read2st64_b32 v[116:117], v118 offset0:12 offset1:13
	ds_read2st64_b32 v[118:119], v118 offset0:14 offset1:15
	v_readlane_b32 s13, v253, 27
	s_nop 1
	v_add_u32_e32 v120, s13, v133
	ds_read2st64_b32 v[150:151], v120 offset1:1
	ds_read2st64_b32 v[152:153], v120 offset0:8 offset1:9
	ds_read2st64_b32 v[154:155], v120 offset0:2 offset1:3
	ds_read2st64_b32 v[156:157], v120 offset0:4 offset1:5
	ds_read2st64_b32 v[158:159], v120 offset0:6 offset1:7
	ds_read2st64_b32 v[160:161], v120 offset0:10 offset1:11
	s_waitcnt lgkmcnt(6)
	v_add_f32_e32 v104, 0, v104
	v_add_f32_e32 v106, 0, v106
	v_add_f32_e32 v104, v104, v105
	v_add_f32_e32 v105, v106, v107
	ds_read2st64_b32 v[162:163], v120 offset0:12 offset1:13
	ds_read2st64_b32 v[164:165], v120 offset0:14 offset1:15
	v_add_f32_e32 v104, v104, v108
	v_add_f32_e32 v105, v105, v114
	v_add_f32_e32 v104, v104, v109
	v_add_f32_e32 v105, v105, v115
	v_add_f32_e32 v104, v104, v110
	v_add_f32_e32 v105, v105, v116
	v_add_f32_e32 v104, v104, v111
	v_add_f32_e32 v105, v105, v117
	v_add_f32_e32 v104, v104, v112
	v_add_f32_e32 v105, v105, v118
	v_add_f32_e32 v104, v104, v113
	v_add_f32_e32 v105, v105, v119
	s_waitcnt lgkmcnt(0)
	v_add_f32_e32 v121, 0, v150
	v_add_f32_e32 v122, 0, v152
	v_add_f32_e32 v121, v121, v151
	v_add_f32_e32 v122, v122, v153
	v_add_f32_e32 v121, v121, v154
	v_add_f32_e32 v122, v122, v160
	v_add_f32_e32 v121, v121, v155
	v_add_f32_e32 v122, v122, v161
	v_add_f32_e32 v121, v121, v156
	v_add_f32_e32 v122, v122, v162
	v_add_f32_e32 v121, v121, v157
	v_add_f32_e32 v122, v122, v163
	v_add_f32_e32 v121, v121, v158
	v_add_f32_e32 v122, v122, v164
	v_add_f32_e32 v121, v121, v159
	v_add_f32_e32 v122, v122, v165
	v_add_f32_dpp v104, v104, v104 quad_perm:[1,0,3,2] row_mask:0xf bank_mask:0xf
	v_add_f32_dpp v105, v105, v105 quad_perm:[1,0,3,2] row_mask:0xf bank_mask:0xf
	v_add_f32_dpp v121, v121, v121 quad_perm:[1,0,3,2] row_mask:0xf bank_mask:0xf
	v_add_f32_dpp v122, v122, v122 quad_perm:[1,0,3,2] row_mask:0xf bank_mask:0xf
	v_add_f32_dpp v104, v104, v104 quad_perm:[2,3,0,1] row_mask:0xf bank_mask:0xf
	v_add_f32_dpp v105, v105, v105 quad_perm:[2,3,0,1] row_mask:0xf bank_mask:0xf
	v_add_f32_dpp v121, v121, v121 quad_perm:[2,3,0,1] row_mask:0xf bank_mask:0xf
	v_add_f32_dpp v122, v122, v122 quad_perm:[2,3,0,1] row_mask:0xf bank_mask:0xf
	v_add_f32_dpp v104, v104, v104 row_half_mirror row_mask:0xf bank_mask:0xf
	v_add_f32_dpp v105, v105, v105 row_half_mirror row_mask:0xf bank_mask:0xf
	v_add_f32_dpp v121, v121, v121 row_half_mirror row_mask:0xf bank_mask:0xf
	v_add_f32_dpp v122, v122, v122 row_half_mirror row_mask:0xf bank_mask:0xf
	v_add_f32_dpp v104, v104, v104 row_mirror row_mask:0xf bank_mask:0xf
	v_add_f32_dpp v105, v105, v105 row_mirror row_mask:0xf bank_mask:0xf
	v_add_f32_dpp v121, v121, v121 row_mirror row_mask:0xf bank_mask:0xf
	v_add_f32_dpp v122, v122, v122 row_mirror row_mask:0xf bank_mask:0xf
	v_add_f32_dpp v104, v104, v104 row_bcast:15 row_mask:0xa bank_mask:0xf
	v_add_f32_dpp v105, v105, v105 row_bcast:15 row_mask:0xa bank_mask:0xf
	v_add_f32_dpp v121, v121, v121 row_bcast:15 row_mask:0xa bank_mask:0xf
	v_add_f32_dpp v122, v122, v122 row_bcast:15 row_mask:0xa bank_mask:0xf
	v_add_f32_dpp v104, v104, v104 row_bcast:31 row_mask:0xc bank_mask:0xf
	v_add_f32_dpp v105, v105, v105 row_bcast:31 row_mask:0xc bank_mask:0xf
	v_add_f32_dpp v121, v121, v121 row_bcast:31 row_mask:0xc bank_mask:0xf
	v_add_f32_dpp v122, v122, v122 row_bcast:31 row_mask:0xc bank_mask:0xf
	v_readlane_b32 s4, v104, 63
	v_readlane_b32 s5, v105, 63
	v_readlane_b32 s6, v121, 63
	v_readlane_b32 s8, v122, 63
	s_and_saveexec_b64 s[34:35], s[40:41]
	s_cbranch_execz .LBB0_744
	v_mov_b32_e32 v104, s4
	v_mov_b32_e32 v106, s5
	v_mul_f32_e32 v104, 0x3a800000, v104
	s_mov_b32 s13, 0x3a800000
	v_mul_f32_e32 v105, v104, v104
	v_mov_b32_e32 v108, s6
	v_fma_f32 v105, v106, s13, -v105
	v_mov_b32_e32 v107, s8
	v_mul_f32_e32 v108, 0x3a800000, v108
	v_add_f32_e32 v105, 0x358637bd, v105
	v_mul_f32_e32 v109, v108, v108
	v_rsq_f32_e32 v105, v105
	v_fma_f32 v109, v107, s13, -v109
	v_readlane_b32 s13, v253, 29
	v_add_f32_e32 v109, 0x358637bd, v109
	s_add_i32 s13, s13, 0x10000
	v_rsq_f32_e32 v109, v109
	v_mov_b32_e32 v106, s13
	v_readlane_b32 s13, v253, 28
	ds_write_b64 v106, v[104:105]
	s_add_i32 s13, s13, 0x10000
	v_mov_b32_e32 v107, s13
	ds_write_b64 v107, v[108:109]
	s_branch .LBB0_744

; __device__ __forceinline__ unsigned cvt_pk_bf16(float lo, float hi) { const f32x2 v = {lo, hi}; const bf16x2_t b = __builtin_convertvector(v, bf16x2_t); return __builtin_bit_cast(unsigned, b); }
; __device__ __forceinline__ int lane_id() { return (int)__builtin_amdgcn_mbcnt_hi(~0u, __builtin_amdgcn_mbcnt_lo(~0u, 0u)); }
; __device__ __forceinline__ void rms_rows4_to_bf16(const float* x0row, size_t rstride, const float* g, bf16_t* o0row, int lane) {
;     ...
;     for (int r = 0; r < 4; ++r) { const f32x4* xr = (const f32x4*)(x0row + r * rstride) + lane; s[r] = 0.f;
; #pragma unroll
;         for (int j = 0; j < 4; ++j) v[r][j] = xr[64 * j]; }
; #pragma unroll
;     for (int r = 0; r < 4; ++r)
; #pragma unroll
;         for (int j = 0; j < 4; ++j) s[r] += (v[r][j].x * v[r][j].x + v[r][j].y * v[r][j].y) + (v[r][j].z * v[r][j].z + v[r][j].w * v[r][j].w);
;     { int lid = lane_id(); asm volatile("" : "+v"(lid));
; #pragma unroll
;       for (int o = 1; o < 64; o <<= 1)
; #pragma unroll
;           for (int r = 0; r < 4; ++r) s[r] += __int_as_float(__builtin_amdgcn_ds_bpermute((lid ^ o) << 2, __float_as_int(s[r]))); }
;     const f32x4* gr = (const f32x4*)g + lane;
; #pragma unroll
;     for (int r = 0; r < 4; ++r) { const float rstd = __builtin_amdgcn_rsqf(s[r] * (1.f / DM) + EPS); u32x2* o8 = (u32x2*)(o0row + r * rstride) + lane;
; #pragma unroll
;         for (int j = 0; j < 4; ++j) { const f32x4 gg = gr[64 * j]; u32x2 w; w.x = cvt_pk_bf16(v[r][j].x * rstd * gg.x, v[r][j].y * rstd * gg.y); w.y = cvt_pk_bf16(v[r][j].z * rstd * gg.z, v[r][j].w * rstd * gg.w); o8[64 * j] = w; } }
.LBB0_884:
	global_load_dwordx4 v[62:65], v[70:71], off
	global_load_dwordx4 v[58:61], v[70:71], off offset:1024
	global_load_dwordx4 v[50:53], v[70:71], off offset:3072
	global_load_dwordx4 v[54:57], v[70:71], off offset:2048
	v_lshl_add_u64 v[2:3], v[70:71], 0, s[8:9]
	global_load_dwordx4 v[46:49], v[2:3], off
	global_load_dwordx4 v[42:45], v[2:3], off offset:1024
	global_load_dwordx4 v[38:41], v[2:3], off offset:2048
	global_load_dwordx4 v[34:37], v[2:3], off offset:3072
	v_lshl_add_u64 v[2:3], v[2:3], 0, s[8:9]
	v_mov_b32_e32 v74, v195
	v_lshl_add_u64 v[14:15], v[2:3], 0, s[8:9]
	global_load_dwordx4 v[30:33], v[2:3], off
	global_load_dwordx4 v[26:29], v[2:3], off offset:1024
	global_load_dwordx4 v[22:25], v[2:3], off offset:2048
	global_load_dwordx4 v[10:13], v[2:3], off offset:3072
	s_add_i32 s38, s38, s0
	global_load_dwordx4 v[2:5], v[14:15], off
	v_lshl_add_u64 v[70:71], v[70:71], 0, s[10:11]
	s_cmpk_gt_i32 s38, 0x3fff
	s_waitcnt vmcnt(0)
	v_pk_mul_f32 v[6:7], v[64:65], v[64:65]
	v_pk_mul_f32 v[16:17], v[62:63], v[62:63]
	v_pk_mul_f32 v[8:9], v[60:61], v[60:61]
	v_pk_mul_f32 v[18:19], v[58:59], v[58:59]
	v_pk_mov_b32 v[20:21], v[16:17], v[6:7] op_sel:[1,0]
	v_mov_b32_e32 v17, v7
	v_mul_f32_e32 v0, v55, v55
	v_pk_mov_b32 v[72:73], v[18:19], v[8:9] op_sel:[1,0]
	v_mov_b32_e32 v19, v9
	v_pk_add_f32 v[16:17], v[20:21], v[16:17]
	v_pk_fma_f32 v[20:21], v[54:55], v[54:55], v[0:1] op_sel_hi:[1,1,0]
	v_mul_f32_e32 v0, v57, v57
	v_mul_f32_e32 v75, v52, v52
	v_mul_f32_e32 v76, v53, v53
	v_pk_add_f32 v[18:19], v[72:73], v[18:19]
	v_pk_fma_f32 v[72:73], v[56:57], v[56:57], v[0:1] op_sel_hi:[1,1,0]
	v_mov_b32_e32 v21, v75
	v_mov_b32_e32 v73, v76
	v_mul_f32_e32 v0, v50, v50
	v_pk_add_f32 v[72:73], v[20:21], v[72:73]
	v_mul_f32_e32 v20, v51, v51
	v_pk_add_f32 v[16:17], v[16:17], v[16:17] op_sel:[0,1] op_sel_hi:[1,0]
	v_pk_add_f32 v[18:19], v[18:19], v[18:19] op_sel:[0,1] op_sel_hi:[1,0]
	v_mov_b32_e32 v17, v0
	v_mov_b32_e32 v19, v20
	v_pk_add_f32 v[16:17], v[16:17], v[18:19]
	global_load_dwordx4 v[6:9], v[14:15], off offset:1024
	global_load_dwordx4 v[18:21], v[14:15], off offset:2048
	v_pk_add_f32 v[72:73], v[16:17], v[72:73]
	global_load_dwordx4 v[14:17], v[14:15], off offset:3072
	global_load_dwordx4 v[80:83], v[66:67], off
	v_lshlrev_b32_e32 v0, 2, v74
	v_xor_b32_e32 v74, 4, v0
	v_add_f32_e32 v72, v72, v73
	v_xor_b32_e32 v75, 8, v0
	v_xor_b32_e32 v76, 16, v0
	v_xor_b32_e32 v77, 32, v0
	v_xor_b32_e32 v78, 64, v0
	s_nop 1
	v_add_f32_dpp v72, v72, v72 quad_perm:[1,0,3,2] row_mask:0xf bank_mask:0xf
	v_xor_b32_e32 v79, 0x80, v0
	s_nop 1
	v_add_f32_dpp v72, v72, v72 quad_perm:[2,3,0,1] row_mask:0xf bank_mask:0xf
	s_nop 1
	v_add_f32_dpp v72, v72, v72 row_half_mirror row_mask:0xf bank_mask:0xf
	s_nop 1
	v_add_f32_dpp v72, v72, v72 row_mirror row_mask:0xf bank_mask:0xf
	s_nop 1
	v_add_f32_dpp v72, v72, v72 row_bcast:15 row_mask:0xa bank_mask:0xf
	s_nop 1
	v_add_f32_dpp v72, v72, v72 row_bcast:31 row_mask:0xc bank_mask:0xf
	s_nop 0
	v_readlane_b32 s13, v72, 63
	s_nop 1
	v_mov_b32_e32 v0, s13
	v_fmamk_f32 v0, v0, 0x3a800000, v193
	v_rsq_f32_e32 v0, v0
	s_nop 0
	v_pk_mul_f32 v[72:73], v[62:63], v[0:1] op_sel_hi:[1,0]
	v_pk_mul_f32 v[62:63], v[64:65], v[0:1] op_sel_hi:[1,0]
	v_pk_mul_f32 v[50:51], v[50:51], v[0:1] op_sel_hi:[1,0]
	v_pk_mul_f32 v[52:53], v[52:53], v[0:1] op_sel_hi:[1,0]
	s_waitcnt vmcnt(0)
	s_waitcnt vmcnt(0)
	v_pk_mul_f32 v[64:65], v[80:81], v[72:73]
	v_pk_mul_f32 v[62:63], v[82:83], v[62:63]
	v_pk_mul_f32 v[72:73], v[58:59], v[0:1] op_sel_hi:[1,0]
	v_cvt_pk_bf16_f32 v58, v64, v65
	v_cvt_pk_bf16_f32 v59, v62, v63
	global_store_dwordx2 v[68:69], v[58:59], off
	v_pk_mul_f32 v[80:81], v[60:61], v[0:1] op_sel_hi:[1,0]
	v_pk_mul_f32 v[62:63], v[54:55], v[0:1] op_sel_hi:[1,0]
	v_pk_mul_f32 v[64:65], v[56:57], v[0:1] op_sel_hi:[1,0]
	v_mul_f32_e32 v0, v39, v39
	v_pk_mul_f32 v[58:59], v[72:73], v[154:155]
	v_pk_mul_f32 v[60:61], v[80:81], v[156:157]
	v_cvt_pk_bf16_f32 v54, v58, v59
	v_cvt_pk_bf16_f32 v55, v60, v61
	global_store_dwordx2 v[68:69], v[54:55], off offset:512
	v_pk_mul_f32 v[58:59], v[48:49], v[48:49]
	v_pk_mul_f32 v[60:61], v[46:47], v[46:47]
	v_pk_mul_f32 v[54:55], v[62:63], v[158:159]
	v_pk_mul_f32 v[56:57], v[64:65], v[160:161]
	v_cvt_pk_bf16_f32 v54, v54, v55
	v_cvt_pk_bf16_f32 v55, v56, v57
	global_store_dwordx2 v[68:69], v[54:55], off offset:1024
	v_pk_mul_f32 v[62:63], v[44:45], v[44:45]
	v_pk_mul_f32 v[50:51], v[50:51], v[162:163]
	v_pk_mul_f32 v[52:53], v[52:53], v[164:165]
	v_cvt_pk_bf16_f32 v50, v50, v51
	v_cvt_pk_bf16_f32 v51, v52, v53
	global_store_dwordx2 v[68:69], v[50:51], off offset:1536
	v_pk_mul_f32 v[54:55], v[42:43], v[42:43]
	v_pk_mov_b32 v[56:57], v[60:61], v[58:59] op_sel:[1,0]
	v_mov_b32_e32 v61, v59
	v_pk_mov_b32 v[58:59], v[54:55], v[62:63] op_sel:[1,0]
	v_mov_b32_e32 v55, v63
	v_pk_add_f32 v[54:55], v[58:59], v[54:55]
	v_mul_f32_e32 v58, v41, v41
	v_mul_f32_e32 v62, v36, v36
	v_mul_f32_e32 v63, v37, v37
	v_pk_add_f32 v[56:57], v[56:57], v[60:61]
	v_pk_fma_f32 v[60:61], v[38:39], v[38:39], v[0:1] op_sel_hi:[1,1,0]
	v_pk_fma_f32 v[58:59], v[40:41], v[40:41], v[58:59] op_sel_hi:[1,1,0]
	v_mov_b32_e32 v61, v62
	v_mov_b32_e32 v59, v63
	v_pk_add_f32 v[58:59], v[60:61], v[58:59]
	v_mul_f32_e32 v0, v34, v34
	v_mul_f32_e32 v60, v35, v35
	v_pk_add_f32 v[56:57], v[56:57], v[56:57] op_sel:[0,1] op_sel_hi:[1,0]
	v_pk_add_f32 v[54:55], v[54:55], v[54:55] op_sel:[0,1] op_sel_hi:[1,0]
	v_mov_b32_e32 v57, v0
	v_mov_b32_e32 v55, v60
	v_pk_add_f32 v[54:55], v[56:57], v[54:55]
	v_lshl_add_u64 v[62:63], v[68:69], 0, s[6:7]
	v_pk_add_f32 v[54:55], v[54:55], v[58:59]
	v_lshl_add_u64 v[68:69], v[68:69], 0, s[4:5]
; __device__ __forceinline__ unsigned cvt_pk_bf16(float lo, float hi) { const f32x2 v = {lo, hi}; const bf16x2_t b = __builtin_convertvector(v, bf16x2_t); return __builtin_bit_cast(unsigned, b); }
; __device__ __forceinline__ int lane_id() { return (int)__builtin_amdgcn_mbcnt_hi(~0u, __builtin_amdgcn_mbcnt_lo(~0u, 0u)); }
; __device__ __forceinline__ void rms_rows4_to_bf16(const float* x0row, size_t rstride, const float* g, bf16_t* o0row, int lane) {
;     ...
;     for (int r = 0; r < 4; ++r) { const f32x4* xr = (const f32x4*)(x0row + r * rstride) + lane; s[r] = 0.f;
; #pragma unroll
;         for (int j = 0; j < 4; ++j) v[r][j] = xr[64 * j]; }
; #pragma unroll
;     for (int r = 0; r < 4; ++r)
; #pragma unroll
;         for (int j = 0; j < 4; ++j) s[r] += (v[r][j].x * v[r][j].x + v[r][j].y * v[r][j].y) + (v[r][j].z * v[r][j].z + v[r][j].w * v[r][j].w);
;     { int lid = lane_id(); asm volatile("" : "+v"(lid));
; #pragma unroll
;       for (int o = 1; o < 64; o <<= 1)
; #pragma unroll
;           for (int r = 0; r < 4; ++r) s[r] += __int_as_float(__builtin_amdgcn_ds_bpermute((lid ^ o) << 2, __float_as_int(s[r]))); }
;     const f32x4* gr = (const f32x4*)g + lane;
; #pragma unroll
;     for (int r = 0; r < 4; ++r) { const float rstd = __builtin_amdgcn_rsqf(s[r] * (1.f / DM) + EPS); u32x2* o8 = (u32x2*)(o0row + r * rstride) + lane;
; #pragma unroll
;         for (int j = 0; j < 4; ++j) { const f32x4 gg = gr[64 * j]; u32x2 w; w.x = cvt_pk_bf16(v[r][j].x * rstd * gg.x, v[r][j].y * rstd * gg.y); w.y = cvt_pk_bf16(v[r][j].z * rstd * gg.z, v[r][j].w * rstd * gg.w); o8[64 * j] = w; } }
	v_add_f32_e32 v0, v54, v55
	v_mul_f32_e32 v55, v13, v13
	s_nop 1
	v_add_f32_dpp v0, v0, v0 quad_perm:[1,0,3,2] row_mask:0xf bank_mask:0xf
	s_nop 1
	v_add_f32_dpp v0, v0, v0 quad_perm:[2,3,0,1] row_mask:0xf bank_mask:0xf
	s_nop 1
	v_add_f32_dpp v0, v0, v0 row_half_mirror row_mask:0xf bank_mask:0xf
	s_nop 1
	v_add_f32_dpp v0, v0, v0 row_mirror row_mask:0xf bank_mask:0xf
	s_nop 1
	v_add_f32_dpp v0, v0, v0 row_bcast:15 row_mask:0xa bank_mask:0xf
	s_nop 1
	v_add_f32_dpp v0, v0, v0 row_bcast:31 row_mask:0xc bank_mask:0xf
	s_nop 0
	v_readlane_b32 s13, v0, 63
	s_nop 1
	v_mov_b32_e32 v0, s13
	v_fmamk_f32 v0, v0, 0x3a800000, v193
	v_rsq_f32_e32 v0, v0
	v_mul_f32_e32 v54, v12, v12
	v_pk_mul_f32 v[46:47], v[46:47], v[0:1] op_sel_hi:[1,0]
	v_pk_mul_f32 v[48:49], v[48:49], v[0:1] op_sel_hi:[1,0]
	v_pk_mul_f32 v[42:43], v[42:43], v[0:1] op_sel_hi:[1,0]
	v_pk_mul_f32 v[44:45], v[44:45], v[0:1] op_sel_hi:[1,0]
	v_pk_mul_f32 v[38:39], v[38:39], v[0:1] op_sel_hi:[1,0]
	v_pk_mul_f32 v[40:41], v[40:41], v[0:1] op_sel_hi:[1,0]
	v_pk_mul_f32 v[34:35], v[34:35], v[0:1] op_sel_hi:[1,0]
	v_pk_mul_f32 v[36:37], v[36:37], v[0:1] op_sel_hi:[1,0]
	v_mul_f32_e32 v0, v23, v23
	v_pk_mul_f32 v[46:47], v[46:47], v[150:151]
	v_pk_mul_f32 v[48:49], v[48:49], v[152:153]
	v_cvt_pk_bf16_f32 v46, v46, v47
	v_cvt_pk_bf16_f32 v47, v48, v49
	global_store_dwordx2 v[62:63], v[46:47], off
	v_pk_mul_f32 v[50:51], v[26:27], v[26:27]
	v_mul_f32_e32 v52, v10, v10
	v_mul_f32_e32 v53, v11, v11
	v_pk_mul_f32 v[42:43], v[42:43], v[154:155]
	v_pk_mul_f32 v[44:45], v[44:45], v[156:157]
	v_cvt_pk_bf16_f32 v42, v42, v43
	v_cvt_pk_bf16_f32 v43, v44, v45
	global_store_dwordx2 v[62:63], v[42:43], off offset:512
	v_pk_mul_f32 v[46:47], v[30:31], v[30:31]
	v_pk_mul_f32 v[48:49], v[28:29], v[28:29]
	v_pk_mul_f32 v[38:39], v[38:39], v[158:159]
	v_pk_mul_f32 v[40:41], v[40:41], v[160:161]
	v_cvt_pk_bf16_f32 v38, v38, v39
	v_cvt_pk_bf16_f32 v39, v40, v41
	global_store_dwordx2 v[62:63], v[38:39], off offset:1024
	v_pk_mul_f32 v[44:45], v[32:33], v[32:33]
	v_lshl_add_u64 v[42:43], v[62:63], 0, s[6:7]
	v_pk_mul_f32 v[34:35], v[34:35], v[162:163]
	v_pk_mul_f32 v[36:37], v[36:37], v[164:165]
	v_cvt_pk_bf16_f32 v34, v34, v35
	v_cvt_pk_bf16_f32 v35, v36, v37
	global_store_dwordx2 v[62:63], v[34:35], off offset:1536
	v_pk_mov_b32 v[40:41], v[46:47], v[44:45] op_sel:[1,0]
	v_mov_b32_e32 v47, v45
	v_pk_mov_b32 v[44:45], v[50:51], v[48:49] op_sel:[1,0]
	v_mov_b32_e32 v51, v49
	v_mul_f32_e32 v38, v25, v25
	v_pk_add_f32 v[40:41], v[40:41], v[46:47]
	v_pk_add_f32 v[44:45], v[44:45], v[50:51]
	v_pk_fma_f32 v[48:49], v[22:23], v[22:23], v[0:1] op_sel_hi:[1,1,0]
	v_pk_fma_f32 v[38:39], v[24:25], v[24:25], v[38:39] op_sel_hi:[1,1,0]
	v_pk_add_f32 v[40:41], v[40:41], v[40:41] op_sel:[0,1] op_sel_hi:[1,0]
	v_pk_add_f32 v[44:45], v[44:45], v[44:45] op_sel:[0,1] op_sel_hi:[1,0]
	v_mov_b32_e32 v49, v54
	v_mov_b32_e32 v39, v55
	v_mov_b32_e32 v41, v52
	v_mov_b32_e32 v45, v53
	v_pk_add_f32 v[38:39], v[48:49], v[38:39]
	v_pk_add_f32 v[40:41], v[40:41], v[44:45]
	s_nop 0
	v_pk_add_f32 v[38:39], v[40:41], v[38:39]
	s_nop 0
	v_add_f32_e32 v0, v38, v39
	v_mul_f32_e32 v39, v17, v17
	s_nop 1
	v_add_f32_dpp v0, v0, v0 quad_perm:[1,0,3,2] row_mask:0xf bank_mask:0xf
	s_nop 1
	v_add_f32_dpp v0, v0, v0 quad_perm:[2,3,0,1] row_mask:0xf bank_mask:0xf
	s_nop 1
	v_add_f32_dpp v0, v0, v0 row_half_mirror row_mask:0xf bank_mask:0xf
	s_nop 1
	v_add_f32_dpp v0, v0, v0 row_mirror row_mask:0xf bank_mask:0xf
	s_nop 1
	v_add_f32_dpp v0, v0, v0 row_bcast:15 row_mask:0xa bank_mask:0xf
	s_nop 1
	v_add_f32_dpp v0, v0, v0 row_bcast:31 row_mask:0xc bank_mask:0xf
	s_nop 0
	v_readlane_b32 s13, v0, 63
	s_nop 1
	v_mov_b32_e32 v0, s13
	v_fmamk_f32 v0, v0, 0x3a800000, v193
	v_rsq_f32_e32 v0, v0
	v_mul_f32_e32 v38, v16, v16
	v_pk_mul_f32 v[30:31], v[30:31], v[0:1] op_sel_hi:[1,0]
	v_pk_mul_f32 v[32:33], v[32:33], v[0:1] op_sel_hi:[1,0]
	v_pk_mul_f32 v[26:27], v[26:27], v[0:1] op_sel_hi:[1,0]
	v_pk_mul_f32 v[28:29], v[28:29], v[0:1] op_sel_hi:[1,0]
; __device__ __forceinline__ unsigned cvt_pk_bf16(float lo, float hi) { const f32x2 v = {lo, hi}; const bf16x2_t b = __builtin_convertvector(v, bf16x2_t); return __builtin_bit_cast(unsigned, b); }
; __device__ __forceinline__ int lane_id() { return (int)__builtin_amdgcn_mbcnt_hi(~0u, __builtin_amdgcn_mbcnt_lo(~0u, 0u)); }
; __device__ __forceinline__ void rms_rows4_to_bf16(const float* x0row, size_t rstride, const float* g, bf16_t* o0row, int lane) {
;     ...
;     for (int r = 0; r < 4; ++r) { const f32x4* xr = (const f32x4*)(x0row + r * rstride) + lane; s[r] = 0.f;
; #pragma unroll
;         for (int j = 0; j < 4; ++j) v[r][j] = xr[64 * j]; }
; #pragma unroll
;     for (int r = 0; r < 4; ++r)
; #pragma unroll
;         for (int j = 0; j < 4; ++j) s[r] += (v[r][j].x * v[r][j].x + v[r][j].y * v[r][j].y) + (v[r][j].z * v[r][j].z + v[r][j].w * v[r][j].w);
;     { int lid = lane_id(); asm volatile("" : "+v"(lid));
; #pragma unroll
;       for (int o = 1; o < 64; o <<= 1)
; #pragma unroll
;           for (int r = 0; r < 4; ++r) s[r] += __int_as_float(__builtin_amdgcn_ds_bpermute((lid ^ o) << 2, __float_as_int(s[r]))); }
;     const f32x4* gr = (const f32x4*)g + lane;
; #pragma unroll
;     for (int r = 0; r < 4; ++r) { const float rstd = __builtin_amdgcn_rsqf(s[r] * (1.f / DM) + EPS); u32x2* o8 = (u32x2*)(o0row + r * rstride) + lane;
; #pragma unroll
;         for (int j = 0; j < 4; ++j) { const f32x4 gg = gr[64 * j]; u32x2 w; w.x = cvt_pk_bf16(v[r][j].x * rstd * gg.x, v[r][j].y * rstd * gg.y); w.y = cvt_pk_bf16(v[r][j].z * rstd * gg.z, v[r][j].w * rstd * gg.w); o8[64 * j] = w; } }
	v_pk_mul_f32 v[22:23], v[22:23], v[0:1] op_sel_hi:[1,0]
	v_pk_mul_f32 v[24:25], v[24:25], v[0:1] op_sel_hi:[1,0]
	v_pk_mul_f32 v[10:11], v[10:11], v[0:1] op_sel_hi:[1,0]
	v_pk_mul_f32 v[12:13], v[12:13], v[0:1] op_sel_hi:[1,0]
	v_mul_f32_e32 v0, v19, v19
	v_pk_mul_f32 v[30:31], v[30:31], v[150:151]
	v_pk_mul_f32 v[32:33], v[32:33], v[152:153]
	v_cvt_pk_bf16_f32 v30, v30, v31
	v_cvt_pk_bf16_f32 v31, v32, v33
	global_store_dwordx2 v[42:43], v[30:31], off
	v_mul_f32_e32 v36, v14, v14
	v_mul_f32_e32 v37, v15, v15
	v_pk_mul_f32 v[26:27], v[26:27], v[154:155]
	v_pk_mul_f32 v[28:29], v[28:29], v[156:157]
	v_cvt_pk_bf16_f32 v26, v26, v27
	v_cvt_pk_bf16_f32 v27, v28, v29
	global_store_dwordx2 v[42:43], v[26:27], off offset:512
	v_pk_mul_f32 v[30:31], v[6:7], v[6:7]
	v_mul_f32_e32 v32, v21, v21
	v_pk_fma_f32 v[32:33], v[20:21], v[20:21], v[32:33] op_sel_hi:[1,1,0]
	v_pk_mul_f32 v[22:23], v[22:23], v[158:159]
	v_pk_mul_f32 v[24:25], v[24:25], v[160:161]
	v_cvt_pk_bf16_f32 v22, v22, v23
	v_cvt_pk_bf16_f32 v23, v24, v25
	global_store_dwordx2 v[42:43], v[22:23], off offset:1024
	v_pk_mul_f32 v[28:29], v[8:9], v[8:9]
	v_mov_b32_e32 v33, v39
	v_lshl_add_u64 v[26:27], v[42:43], 0, s[6:7]
	v_pk_mul_f32 v[10:11], v[10:11], v[162:163]
	v_pk_mul_f32 v[12:13], v[12:13], v[164:165]
	v_cvt_pk_bf16_f32 v10, v10, v11
	v_cvt_pk_bf16_f32 v11, v12, v13
	global_store_dwordx2 v[42:43], v[10:11], off offset:1536
	v_pk_mul_f32 v[22:23], v[4:5], v[4:5]
	v_pk_mul_f32 v[24:25], v[2:3], v[2:3]
	s_nop 0
	v_pk_mov_b32 v[34:35], v[24:25], v[22:23] op_sel:[1,0]
	v_mov_b32_e32 v25, v23
	v_pk_mov_b32 v[22:23], v[30:31], v[28:29] op_sel:[1,0]
	v_mov_b32_e32 v31, v29
	v_pk_add_f32 v[24:25], v[34:35], v[24:25]
	v_pk_add_f32 v[22:23], v[22:23], v[30:31]
	v_pk_fma_f32 v[28:29], v[18:19], v[18:19], v[0:1] op_sel_hi:[1,1,0]
	v_pk_add_f32 v[24:25], v[24:25], v[24:25] op_sel:[0,1] op_sel_hi:[1,0]
	v_pk_add_f32 v[22:23], v[22:23], v[22:23] op_sel:[0,1] op_sel_hi:[1,0]
	v_mov_b32_e32 v29, v38
	v_mov_b32_e32 v25, v36
	v_mov_b32_e32 v23, v37
	v_pk_add_f32 v[28:29], v[28:29], v[32:33]
	v_pk_add_f32 v[22:23], v[24:25], v[22:23]
	s_nop 0
	v_pk_add_f32 v[22:23], v[22:23], v[28:29]
	s_nop 0
	v_add_f32_e32 v0, v22, v23
	s_nop 1
	v_add_f32_dpp v0, v0, v0 quad_perm:[1,0,3,2] row_mask:0xf bank_mask:0xf
	s_nop 1
	v_add_f32_dpp v0, v0, v0 quad_perm:[2,3,0,1] row_mask:0xf bank_mask:0xf
	s_nop 1
	v_add_f32_dpp v0, v0, v0 row_half_mirror row_mask:0xf bank_mask:0xf
	s_nop 1
	v_add_f32_dpp v0, v0, v0 row_mirror row_mask:0xf bank_mask:0xf
	s_nop 1
	v_add_f32_dpp v0, v0, v0 row_bcast:15 row_mask:0xa bank_mask:0xf
	s_nop 1
	v_add_f32_dpp v0, v0, v0 row_bcast:31 row_mask:0xc bank_mask:0xf
	s_nop 0
	v_readlane_b32 s13, v0, 63
	s_nop 1
	v_mov_b32_e32 v0, s13
	v_fmamk_f32 v0, v0, 0x3a800000, v193
	v_rsq_f32_e32 v0, v0
	s_nop 0
	v_pk_mul_f32 v[2:3], v[2:3], v[0:1] op_sel_hi:[1,0]
	v_pk_mul_f32 v[4:5], v[4:5], v[0:1] op_sel_hi:[1,0]
	v_pk_mul_f32 v[6:7], v[6:7], v[0:1] op_sel_hi:[1,0]
	v_pk_mul_f32 v[8:9], v[8:9], v[0:1] op_sel_hi:[1,0]
	v_pk_mul_f32 v[2:3], v[2:3], v[150:151]
	v_pk_mul_f32 v[4:5], v[4:5], v[152:153]
	v_cvt_pk_bf16_f32 v2, v2, v3
	v_cvt_pk_bf16_f32 v3, v4, v5
	global_store_dwordx2 v[26:27], v[2:3], off
	v_pk_mul_f32 v[2:3], v[6:7], v[154:155]
	v_pk_mul_f32 v[4:5], v[8:9], v[156:157]
	v_cvt_pk_bf16_f32 v2, v2, v3
	v_cvt_pk_bf16_f32 v3, v4, v5
	global_store_dwordx2 v[26:27], v[2:3], off offset:512
	v_pk_mul_f32 v[6:7], v[18:19], v[0:1] op_sel_hi:[1,0]
	v_pk_mul_f32 v[8:9], v[20:21], v[0:1] op_sel_hi:[1,0]
	v_pk_mul_f32 v[2:3], v[6:7], v[158:159]
	v_pk_mul_f32 v[4:5], v[8:9], v[160:161]
	v_cvt_pk_bf16_f32 v2, v2, v3
	v_cvt_pk_bf16_f32 v3, v4, v5
	global_store_dwordx2 v[26:27], v[2:3], off offset:1024
	v_pk_mul_f32 v[6:7], v[14:15], v[0:1] op_sel_hi:[1,0]
	v_pk_mul_f32 v[8:9], v[16:17], v[0:1] op_sel_hi:[1,0]
	v_pk_mul_f32 v[2:3], v[6:7], v[162:163]
	v_pk_mul_f32 v[4:5], v[8:9], v[164:165]
	v_cvt_pk_bf16_f32 v2, v2, v3
	v_cvt_pk_bf16_f32 v3, v4, v5
	global_store_dwordx2 v[26:27], v[2:3], off offset:1536
	s_cbranch_scc0 .LBB0_884
